# baseline (speedup 1.0000x reference)
; template <int EPI>
; __device__ __forceinline__ void gemm_phase(int zz, const u16* __restrict__ Wt, const u16* __restrict__ Act, int K, int lda, int nColTiles,
;                            u16* __restrict__ Out, int ldo, int nvalid, char* shm) {
;     ...
;   for (; tile < ntiles; tile += gridDim.x) {
;     int gidx = tile / (8 * nColTiles), rem = tile % (8 * nColTiles);
;     int pm = gidx * 8 + (rem & 7), pn = rem >> 3;
;     int t0 = pm * 256, c0 = pn * 256;
;     f32x4 acc[8][4];
; #pragma unroll
;     for (int m = 0; m < 8; ++m)
; #pragma unroll
;       for (int n = 0; n < 4; ++n) acc[m][n] = f32x4{0.f, 0.f, 0.f, 0.f};
;     gemm_main<8, 4>(zz, acc, Wt + (long)c0 * K, K, Act + (long)t0 * lda, lda, K, shm);
.LBB0_223:
	s_mul_hi_i32 s2, s15, 0x2e8ba2e9
	s_lshr_b32 s3, s2, 31
	s_ashr_i32 s2, s2, 5
	s_add_i32 s2, s2, s3
	s_mul_i32 s3, s2, 0xb0
	s_sub_i32 s3, s15, s3
	s_lshl_b32 s4, s3, 8
	s_lshl_b32 s3, s3, 5
	s_lshl_b32 s7, s2, 11
	s_and_b32 s2, s3, 0xffffff00
	s_ashr_i32 s3, s2, 31
	s_and_b32 s6, s4, 0x700
	s_lshl_b64 s[4:5], s[2:3], 11
	s_add_u32 s36, s40, s4
	s_addc_u32 s37, s41, s5
	s_add_u32 s36, s36, 0x80
	s_addc_u32 s37, s37, 0
	s_or_b32 s4, s7, s6
	s_waitcnt vmcnt(8)
	s_ashr_i32 s5, s4, 31
	s_lshl_b64 s[6:7], s[4:5], 11
	s_add_u32 s38, s66, s6
	s_addc_u32 s39, s67, s7
	s_add_u32 s38, s38, 0x80
	s_addc_u32 s39, s39, 0
	s_mov_b32 s3, 0
	s_mov_b64 s[6:7], 0
	s_waitcnt vmcnt(8) lgkmcnt(0)
	s_barrier
; #define WAIT_V0() asm volatile("s_waitcnt vmcnt(0)" ::: "memory")
; template <int MF, int NF>
; __device__ __forceinline__ void gemm_main(int zz, f32x4 (&acc)[MF][NF], const u16* __restrict__ Wt, int ldw,
;                                           const u16* __restrict__ Act, int lda, int K, char* shm) {
;     ...
;   for (int t = 0; t < nt; ++t) {
;     const int cur = t & 1;
;     if (t + 1 < nt) {
; #pragma unroll
;       for (int i = 0; i < NLD; ++i) {
;         const u16* src = (i < NLA) ? (Wt + (long)(i * 64) * ldw + (t + 1) * 64 + voffA)
;                                    : (Act + (long)((i - NLA) * 64) * lda + (t + 1) * 64 + voffB);
;         __builtin_amdgcn_global_load_lds((const unsigned*)src, (unsigned*)(shm + (cur ^ 1) * STAGE_B + (i * 8 + wid) * 1024), 16, 0, 0);
;       }
;     }
;     const char* sbase = shm + cur * STAGE_B;
;     {
;       constexpr int D = (NF >= 4) ? 3 : ((MF >= 12) ? 6 : 4), RING = D + 1, NSTEP = 2 * MF;
;       bf16x8 Bf[2][NF], Ar[RING];
; #pragma unroll
;       for (int n = 0; n < NF; ++n) Bf[0][n] = *(const bf16x8*)(sbase + boff + (n * 2 + 0) * 1024);
; #pragma unroll
;       for (int j = 0; j < D; ++j) Ar[j % RING] = *(const bf16x8*)(sbase + aoff + ((j % MF) * 2 + (j / MF)) * 1024);
;       __builtin_amdgcn_sched_barrier(0);
;       __builtin_amdgcn_s_setprio(1);
; #pragma unroll
;       for (int i = 0; i < NSTEP; ++i) {
;         const int ks = i / MF, m = i % MF;
;         const int j = i + D;
;         if (j < NSTEP) {
;           const int ksj = j / MF, mj = j % MF;
;           if (mj == 0) {
; #pragma unroll
;             for (int n = 0; n < NF; ++n) Bf[ksj][n] = *(const bf16x8*)(sbase + boff + (n * 2 + ksj) * 1024);
;           }
;           Ar[j % RING] = *(const bf16x8*)(sbase + aoff + (mj * 2 + ksj) * 1024);
;         }
; #pragma unroll
;         for (int n = 0; n < NF; ++n) acc[m][n] = __builtin_amdgcn_mfma_f32_16x16x32_bf16(Ar[i % RING], Bf[ks][n], acc[m][n], 0, 0, 0);
;         __builtin_amdgcn_sched_barrier(0);
;       }
;       __builtin_amdgcn_s_setprio(0);
;     }
;     WAIT_V0();
;     __syncthreads();
	s_and_b32 s5, s3, 0x10000
	s_xor_b32 s8, s5, 0x10000
	s_add_i32 s8, s8, s42
	s_mov_b32 m0, s8
	v_or_b32_e32 v157, s5, v151
	v_add_u32_e32 v178, v157, v153
	v_add_u32_e32 v157, v157, v152
	ds_read_b128 v[174:177], v157
	ds_read_b128 v[158:161], v178 offset:32768
	ds_read_b128 v[162:165], v178 offset:34816
	ds_read_b128 v[166:169], v178 offset:36864
	ds_read_b128 v[170:173], v178 offset:38912
	ds_read_b128 v[192:195], v157 offset:2048
	ds_read_b128 v[196:199], v157 offset:4096
	s_nop 0
	s_waitcnt lgkmcnt(5)
	v_mfma_f32_16x16x32_bf16 v[126:129], v[174:177], v[158:161], 0
	ds_read_b128 v[200:203], v157 offset:6144
	s_waitcnt lgkmcnt(5)
	v_mfma_f32_16x16x32_bf16 v[122:125], v[174:177], v[162:165], 0
	global_load_lds_dwordx4 v179, s[36:37]
	s_waitcnt lgkmcnt(4)
	v_mfma_f32_16x16x32_bf16 v[118:121], v[174:177], v[166:169], 0
	s_add_u32 s36, s36, 0x20000
	s_addc_u32 s37, s37, 0
	s_addk_i32 m0, 0x2000
	s_waitcnt lgkmcnt(3)
	v_mfma_f32_16x16x32_bf16 v[114:117], v[174:177], v[170:173], 0
	s_waitcnt lgkmcnt(2)
	v_mfma_f32_16x16x32_bf16 v[110:113], v[192:195], v[158:161], 0
	ds_read_b128 v[174:177], v157 offset:8192
	v_mfma_f32_16x16x32_bf16 v[106:109], v[192:195], v[162:165], 0
	global_load_lds_dwordx4 v179, s[36:37]
	v_mfma_f32_16x16x32_bf16 v[102:105], v[192:195], v[166:169], 0
	s_add_u32 s36, s36, 0x20000
	s_addc_u32 s37, s37, 0
	s_addk_i32 m0, 0x2000
	v_mfma_f32_16x16x32_bf16 v[98:101], v[192:195], v[170:173], 0
	s_waitcnt lgkmcnt(2)
	v_mfma_f32_16x16x32_bf16 v[94:97], v[196:199], v[158:161], 0
	ds_read_b128 v[192:195], v157 offset:10240
	v_mfma_f32_16x16x32_bf16 v[90:93], v[196:199], v[162:165], 0
	global_load_lds_dwordx4 v179, s[36:37]
	v_mfma_f32_16x16x32_bf16 v[86:89], v[196:199], v[166:169], 0
	s_add_u32 s36, s36, 0x20000
	s_addc_u32 s37, s37, 0
	s_addk_i32 m0, 0x2000
	v_mfma_f32_16x16x32_bf16 v[82:85], v[196:199], v[170:173], 0
	s_waitcnt lgkmcnt(2)
	v_mfma_f32_16x16x32_bf16 v[78:81], v[200:203], v[158:161], 0
	ds_read_b128 v[196:199], v157 offset:12288
	v_mfma_f32_16x16x32_bf16 v[74:77], v[200:203], v[162:165], 0
	global_load_lds_dwordx4 v179, s[36:37]
	v_mfma_f32_16x16x32_bf16 v[70:73], v[200:203], v[166:169], 0
	s_add_u32 s36, s36, 0xfffa0080
	s_addc_u32 s37, s37, -1
	s_addk_i32 m0, 0x2000
	v_mfma_f32_16x16x32_bf16 v[66:69], v[200:203], v[170:173], 0
	s_waitcnt lgkmcnt(2)
	v_mfma_f32_16x16x32_bf16 v[62:65], v[174:177], v[158:161], 0
	ds_read_b128 v[200:203], v157 offset:14336
	v_mfma_f32_16x16x32_bf16 v[58:61], v[174:177], v[162:165], 0
	global_load_lds_dwordx4 v179, s[38:39]
	v_mfma_f32_16x16x32_bf16 v[54:57], v[174:177], v[166:169], 0
	s_add_u32 s38, s38, 0x20000
	s_addc_u32 s39, s39, 0
	s_addk_i32 m0, 0x2000
	v_mfma_f32_16x16x32_bf16 v[50:53], v[174:177], v[170:173], 0
	ds_read_b128 v[174:177], v178 offset:33792
	ds_read_b128 v[204:207], v178 offset:35840
	ds_read_b128 v[208:211], v178 offset:37888
	ds_read_b128 v[212:215], v178 offset:39936
	ds_read_b128 v[216:219], v157 offset:1024
	s_waitcnt lgkmcnt(7)
	v_mfma_f32_16x16x32_bf16 v[46:49], v[192:195], v[158:161], 0
	v_mfma_f32_16x16x32_bf16 v[42:45], v[192:195], v[162:165], 0
	global_load_lds_dwordx4 v179, s[38:39]
	v_mfma_f32_16x16x32_bf16 v[38:41], v[192:195], v[166:169], 0
	s_add_u32 s38, s38, 0x20000
	s_addc_u32 s39, s39, 0
	s_addk_i32 m0, 0x2000
	v_mfma_f32_16x16x32_bf16 v[34:37], v[192:195], v[170:173], 0
	s_waitcnt lgkmcnt(6)
	v_mfma_f32_16x16x32_bf16 v[30:33], v[196:199], v[158:161], 0
	ds_read_b128 v[192:195], v157 offset:3072
	v_mfma_f32_16x16x32_bf16 v[26:29], v[196:199], v[162:165], 0
	global_load_lds_dwordx4 v179, s[38:39]
	v_mfma_f32_16x16x32_bf16 v[22:25], v[196:199], v[166:169], 0
	s_add_u32 s38, s38, 0x20000
	s_addc_u32 s39, s39, 0
	s_addk_i32 m0, 0x2000
	v_mfma_f32_16x16x32_bf16 v[18:21], v[196:199], v[170:173], 0
	s_waitcnt lgkmcnt(6)
	v_mfma_f32_16x16x32_bf16 v[14:17], v[200:203], v[158:161], 0
	ds_read_b128 v[158:161], v157 offset:5120
	v_mfma_f32_16x16x32_bf16 v[10:13], v[200:203], v[162:165], 0
	global_load_lds_dwordx4 v179, s[38:39]
	v_mfma_f32_16x16x32_bf16 v[6:9], v[200:203], v[166:169], 0
	s_add_u32 s38, s38, 0xfffa0080
	s_addc_u32 s39, s39, -1
	v_mfma_f32_16x16x32_bf16 v[2:5], v[200:203], v[170:173], 0
	s_waitcnt lgkmcnt(2)
	v_mfma_f32_16x16x32_bf16 v[126:129], v[216:219], v[174:177], v[126:129]
	ds_read_b128 v[162:165], v157 offset:7168
	v_mfma_f32_16x16x32_bf16 v[122:125], v[216:219], v[204:207], v[122:125]
	v_mfma_f32_16x16x32_bf16 v[118:121], v[216:219], v[208:211], v[118:121]
	v_mfma_f32_16x16x32_bf16 v[114:117], v[216:219], v[212:215], v[114:117]
	s_waitcnt lgkmcnt(2)
	v_mfma_f32_16x16x32_bf16 v[110:113], v[192:195], v[174:177], v[110:113]
	ds_read_b128 v[166:169], v157 offset:9216
	v_mfma_f32_16x16x32_bf16 v[106:109], v[192:195], v[204:207], v[106:109]
	v_mfma_f32_16x16x32_bf16 v[102:105], v[192:195], v[208:211], v[102:105]
	v_mfma_f32_16x16x32_bf16 v[98:101], v[192:195], v[212:215], v[98:101]
	s_waitcnt lgkmcnt(2)
	v_mfma_f32_16x16x32_bf16 v[94:97], v[158:161], v[174:177], v[94:97]
	ds_read_b128 v[170:173], v157 offset:11264
	v_mfma_f32_16x16x32_bf16 v[90:93], v[158:161], v[204:207], v[90:93]
	v_mfma_f32_16x16x32_bf16 v[86:89], v[158:161], v[208:211], v[86:89]
	v_mfma_f32_16x16x32_bf16 v[82:85], v[158:161], v[212:215], v[82:85]
	s_waitcnt lgkmcnt(2)
	v_mfma_f32_16x16x32_bf16 v[78:81], v[162:165], v[174:177], v[78:81]
	ds_read_b128 v[158:161], v157 offset:13312
	v_mfma_f32_16x16x32_bf16 v[74:77], v[162:165], v[204:207], v[74:77]
	v_mfma_f32_16x16x32_bf16 v[70:73], v[162:165], v[208:211], v[70:73]
	v_mfma_f32_16x16x32_bf16 v[66:69], v[162:165], v[212:215], v[66:69]
	s_waitcnt lgkmcnt(2)
	v_mfma_f32_16x16x32_bf16 v[62:65], v[166:169], v[174:177], v[62:65]
	ds_read_b128 v[162:165], v157 offset:15360
	v_mfma_f32_16x16x32_bf16 v[58:61], v[166:169], v[204:207], v[58:61]
	v_mfma_f32_16x16x32_bf16 v[54:57], v[166:169], v[208:211], v[54:57]
	v_mfma_f32_16x16x32_bf16 v[50:53], v[166:169], v[212:215], v[50:53]
	s_waitcnt lgkmcnt(2)
	v_mfma_f32_16x16x32_bf16 v[46:49], v[170:173], v[174:177], v[46:49]
	v_mfma_f32_16x16x32_bf16 v[42:45], v[170:173], v[204:207], v[42:45]
	v_mfma_f32_16x16x32_bf16 v[38:41], v[170:173], v[208:211], v[38:41]
	v_mfma_f32_16x16x32_bf16 v[34:37], v[170:173], v[212:215], v[34:37]
	s_waitcnt lgkmcnt(1)
	v_mfma_f32_16x16x32_bf16 v[30:33], v[158:161], v[174:177], v[30:33]
	v_mfma_f32_16x16x32_bf16 v[26:29], v[158:161], v[204:207], v[26:29]
	v_mfma_f32_16x16x32_bf16 v[22:25], v[158:161], v[208:211], v[22:25]
	v_mfma_f32_16x16x32_bf16 v[18:21], v[158:161], v[212:215], v[18:21]
	s_waitcnt lgkmcnt(0)
	v_mfma_f32_16x16x32_bf16 v[14:17], v[162:165], v[174:177], v[14:17]
	v_mfma_f32_16x16x32_bf16 v[10:13], v[162:165], v[204:207], v[10:13]
	v_mfma_f32_16x16x32_bf16 v[6:9], v[162:165], v[208:211], v[6:9]
	v_mfma_f32_16x16x32_bf16 v[2:5], v[162:165], v[212:215], v[2:5]
	s_nop 0
	s_add_i32 s3, s3, 0x10000
	s_waitcnt vmcnt(0)
	s_add_u32 s6, s6, 0x80
	s_addc_u32 s7, s7, 0
	s_cmpk_lg_i32 s6, 0x780
	s_waitcnt vmcnt(0)
	s_barrier

; template <int MF, int NF>
; __device__ __forceinline__ void gemm_main(int zz, f32x4 (&acc)[MF][NF], const u16* __restrict__ Wt, int ldw,
;                                           const u16* __restrict__ Act, int lda, int K, char* shm) {
;     ...
;         const u16* src = (i < NLA) ? (Wt + (long)(i * 64) * ldw + (t + 1) * 64 + voffA)
;                                    : (Act + (long)((i - NLA) * 64) * lda + (t + 1) * 64 + voffB);
;         __builtin_amdgcn_global_load_lds((const unsigned*)src, (unsigned*)(shm + (cur ^ 1) * STAGE_B + (i * 8 + wid) * 1024), 16, 0, 0);
; template <int EPI>
; __device__ __forceinline__ void gemm_phase(int zz, const u16* __restrict__ Wt, const u16* __restrict__ Act, int K, int lda, int nColTiles,
;                            u16* __restrict__ Out, int ldo, int nvalid, char* shm) {
;     ...
;     int gidx = tile / (8 * nColTiles), rem = tile % (8 * nColTiles);
;     int pm = gidx * 8 + (rem & 7), pn = rem >> 3;
;     int t0 = pm * 256, c0 = pn * 256;
;     f32x4 acc[8][4];
; #pragma unroll
;     for (int m = 0; m < 8; ++m)
; #pragma unroll
;       for (int n = 0; n < 4; ++n) acc[m][n] = f32x4{0.f, 0.f, 0.f, 0.f};
;     gemm_main<8, 4>(zz, acc, Wt + (long)c0 * K, K, Act + (long)t0 * lda, lda, K, shm);
.LBB0_253:
	s_abs_i32 s7, s31
	s_mul_hi_u32 s8, s7, s36
	s_mul_i32 s9, s8, s35
	s_sub_i32 s7, s7, s9
	s_ashr_i32 s5, s31, 31
	s_add_i32 s9, s8, 1
	s_sub_i32 s10, s7, s35
	s_cmp_ge_u32 s7, s35
	s_cselect_b32 s8, s9, s8
	s_cselect_b32 s7, s10, s7
	s_add_i32 s9, s8, 1
	s_cmp_ge_u32 s7, s35
	s_cselect_b32 s7, s9, s8
	s_xor_b32 s7, s7, s5
	s_sub_i32 s43, s7, s5
	s_mul_i32 s8, s43, s35
	s_sub_i32 s8, s31, s8
	s_lshl_b32 s9, s8, 8
	s_lshl_b32 s8, s8, 5
	s_and_b32 s77, s8, 0xffffff00
	s_and_b32 s76, s9, 0x700
	s_ashr_i32 s8, s77, 31
	s_mul_i32 s10, s40, s77
	s_mul_hi_i32 s9, s40, s77
	s_add_u32 s12, s38, s10
	s_addc_u32 s13, s39, s9
	s_lshl_b32 s9, s77, 1
	s_or_b32 s10, s9, 0x80
	s_mul_i32 s8, s29, s8
	s_mul_hi_u32 s11, s29, s10
	s_add_i32 s11, s11, s8
	s_mul_i32 s10, s29, s10
	s_add_u32 s14, s38, s10
	s_addc_u32 s15, s39, s11
	s_or_b32 s10, s9, 0x100
	s_mul_hi_u32 s11, s29, s10
	s_add_i32 s11, s11, s8
	s_mul_i32 s10, s29, s10
	s_add_u32 s16, s38, s10
	s_addc_u32 s17, s39, s11
	s_or_b32 s9, s9, 0x180
	s_mul_hi_u32 s10, s29, s9
	s_add_i32 s10, s10, s8
	s_mul_i32 s8, s29, s9
	s_add_u32 s18, s38, s8
	s_addc_u32 s19, s39, s10
	s_lshl_b32 s7, s7, 11
	s_or_b32 s7, s7, s76
	s_lshl_b32 s5, s5, 11
	s_sub_i32 s5, s7, s5
	s_ashr_i32 s7, s5, 31
	s_mul_i32 s9, s40, s5
	s_mul_hi_i32 s8, s40, s5
	s_add_u32 s20, s41, s9
	s_addc_u32 s21, s42, s8
	s_lshl_b32 s5, s5, 1
	s_or_b32 s8, s5, 0x100
	s_mul_i32 s7, s29, s7
	s_mul_hi_u32 s9, s29, s8
	s_add_i32 s9, s9, s7
	s_mul_i32 s8, s29, s8
	s_add_u32 s22, s41, s8
	s_addc_u32 s23, s42, s9
	s_or_b32 s8, s5, 0x180
	s_mul_hi_u32 s9, s29, s8
	s_add_i32 s9, s9, s7
	s_mul_i32 s8, s29, s8
	s_add_u32 s24, s41, s8
	s_addc_u32 s25, s42, s9
	s_bitset1_b32 s5, 7
	s_mul_hi_u32 s8, s29, s5
	s_nop 0
	s_add_i32 s8, s8, s7
	s_mul_i32 s5, s29, s5
	s_add_u32 s26, s41, s5
	s_addc_u32 s27, s42, s8
	s_mov_b32 s5, 0
	s_mov_b32 s7, 0
	s_waitcnt lgkmcnt(0)
	s_cmp_eq_u32 s45, 1
	s_cbranch_scc1 .Lpl_b16
	s_waitcnt vmcnt(0)
	s_branch .Lpl_bar

; template <int MF, int NF>
; __device__ __forceinline__ void gemm_main(int zz, f32x4 (&acc)[MF][NF], const u16* __restrict__ Wt, int ldw,
;                                           const u16* __restrict__ Act, int lda, int K, char* shm) {
;     ...
;   WAIT_V0();
;   __syncthreads();
;   for (int t = 0; t < nt; ++t) {
;     const int cur = t & 1;
;     if (t + 1 < nt) {
; #pragma unroll
;       for (int i = 0; i < NLD; ++i) {
;         const u16* src = (i < NLA) ? (Wt + (long)(i * 64) * ldw + (t + 1) * 64 + voffA)
;                                    : (Act + (long)((i - NLA) * 64) * lda + (t + 1) * 64 + voffB);
;         __builtin_amdgcn_global_load_lds((const unsigned*)src, (unsigned*)(shm + (cur ^ 1) * STAGE_B + (i * 8 + wid) * 1024), 16, 0, 0);
;       }
;     }
;     const char* sbase = shm + cur * STAGE_B;
;     {
;       constexpr int D = (NF >= 4) ? 3 : ((MF >= 12) ? 6 : 4), RING = D + 1, NSTEP = 2 * MF;
;       bf16x8 Bf[2][NF], Ar[RING];
; #pragma unroll
;       for (int n = 0; n < NF; ++n) Bf[0][n] = *(const bf16x8*)(sbase + boff + (n * 2 + 0) * 1024);
; #pragma unroll
;       for (int j = 0; j < D; ++j) Ar[j % RING] = *(const bf16x8*)(sbase + aoff + ((j % MF) * 2 + (j / MF)) * 1024);
;       __builtin_amdgcn_sched_barrier(0);
;       __builtin_amdgcn_s_setprio(1);
; #pragma unroll
;       for (int i = 0; i < NSTEP; ++i) {
;         const int ks = i / MF, m = i % MF;
;         const int j = i + D;
;         if (j < NSTEP) {
;           const int ksj = j / MF, mj = j % MF;
;           if (mj == 0) {
; #pragma unroll
;             for (int n = 0; n < NF; ++n) Bf[ksj][n] = *(const bf16x8*)(sbase + boff + (n * 2 + ksj) * 1024);
;           }
;           Ar[j % RING] = *(const bf16x8*)(sbase + aoff + (mj * 2 + ksj) * 1024);
;         }
; #pragma unroll
;         for (int n = 0; n < NF; ++n) acc[m][n] = __builtin_amdgcn_mfma_f32_16x16x32_bf16(Ar[i % RING], Bf[ks][n], acc[m][n], 0, 0, 0);
;         __builtin_amdgcn_sched_barrier(0);
;       }
;       __builtin_amdgcn_s_setprio(0);
;     }
;     WAIT_V0();
;     __syncthreads();
; template <int EPI>
; __device__ __forceinline__ void gemm_phase(int zz, const u16* __restrict__ Wt, const u16* __restrict__ Act, int K, int lda, int nColTiles,
;                            u16* __restrict__ Out, int ldo, int nvalid, char* shm) {
;     ...
;     f32x4 acc[8][4];
; #pragma unroll
;     for (int m = 0; m < 8; ++m)
; #pragma unroll
.Lpl_bar:
	s_barrier
	s_and_b32 s8, s5, 0x10000
	s_xor_b32 s9, s8, 0x10000
	s_add_i32 s9, s9, s44
	s_mov_b32 m0, s9
	s_add_i32 s7, s7, 1
	v_or_b32_e32 v0, s8, v147
	v_add_u32_e32 v138, v0, v149
	v_add_u32_e32 v0, v0, v148
	ds_read_b128 v[168:171], v0
	ds_read_b128 v[152:155], v138 offset:32768
	ds_read_b128 v[156:159], v138 offset:34816
	ds_read_b128 v[160:163], v138 offset:36864
	ds_read_b128 v[164:167], v138 offset:38912
	ds_read_b128 v[172:175], v0 offset:2048
	ds_read_b128 v[176:179], v0 offset:4096
	s_nop 0
	s_waitcnt lgkmcnt(5)
	v_mfma_f32_16x16x32_bf16 v[126:129], v[168:171], v[152:155], 0
	ds_read_b128 v[192:195], v0 offset:6144
	s_waitcnt lgkmcnt(5)
	v_mfma_f32_16x16x32_bf16 v[122:125], v[168:171], v[156:159], 0
	global_load_lds_dwordx4 v136, s[12:13]
	s_waitcnt lgkmcnt(4)
	v_mfma_f32_16x16x32_bf16 v[118:121], v[168:171], v[160:163], 0
	s_addk_i32 m0, 0x2000
	s_waitcnt lgkmcnt(3)
	v_mfma_f32_16x16x32_bf16 v[114:117], v[168:171], v[164:167], 0
	s_waitcnt lgkmcnt(2)
	v_mfma_f32_16x16x32_bf16 v[110:113], v[172:175], v[152:155], 0
	ds_read_b128 v[168:171], v0 offset:8192
	v_mfma_f32_16x16x32_bf16 v[106:109], v[172:175], v[156:159], 0
	global_load_lds_dwordx4 v136, s[14:15]
	v_mfma_f32_16x16x32_bf16 v[102:105], v[172:175], v[160:163], 0
	s_addk_i32 m0, 0x2000
	v_mfma_f32_16x16x32_bf16 v[98:101], v[172:175], v[164:167], 0
	s_waitcnt lgkmcnt(2)
	v_mfma_f32_16x16x32_bf16 v[94:97], v[176:179], v[152:155], 0
	ds_read_b128 v[172:175], v0 offset:10240
	v_mfma_f32_16x16x32_bf16 v[90:93], v[176:179], v[156:159], 0
	global_load_lds_dwordx4 v136, s[16:17]
	v_mfma_f32_16x16x32_bf16 v[86:89], v[176:179], v[160:163], 0
	s_addk_i32 m0, 0x2000
	v_mfma_f32_16x16x32_bf16 v[82:85], v[176:179], v[164:167], 0
	s_waitcnt lgkmcnt(2)
	v_mfma_f32_16x16x32_bf16 v[78:81], v[192:195], v[152:155], 0
	ds_read_b128 v[176:179], v0 offset:12288
	v_mfma_f32_16x16x32_bf16 v[74:77], v[192:195], v[156:159], 0
	global_load_lds_dwordx4 v136, s[18:19]
	v_mfma_f32_16x16x32_bf16 v[70:73], v[192:195], v[160:163], 0
	s_addk_i32 m0, 0x2000
	v_mfma_f32_16x16x32_bf16 v[66:69], v[192:195], v[164:167], 0
	s_waitcnt lgkmcnt(2)
	v_mfma_f32_16x16x32_bf16 v[62:65], v[168:171], v[152:155], 0
	ds_read_b128 v[192:195], v0 offset:14336
	v_mfma_f32_16x16x32_bf16 v[58:61], v[168:171], v[156:159], 0
	global_load_lds_dwordx4 v136, s[20:21]
	v_mfma_f32_16x16x32_bf16 v[54:57], v[168:171], v[160:163], 0
	s_addk_i32 m0, 0x2000
	v_mfma_f32_16x16x32_bf16 v[50:53], v[168:171], v[164:167], 0
	ds_read_b128 v[168:171], v138 offset:33792
	ds_read_b128 v[196:199], v138 offset:35840
	ds_read_b128 v[200:203], v138 offset:37888
	ds_read_b128 v[204:207], v138 offset:39936
	ds_read_b128 v[208:211], v0 offset:1024
	s_waitcnt lgkmcnt(7)
	v_mfma_f32_16x16x32_bf16 v[46:49], v[172:175], v[152:155], 0
	v_mfma_f32_16x16x32_bf16 v[42:45], v[172:175], v[156:159], 0
	global_load_lds_dwordx4 v136, s[26:27]
	v_mfma_f32_16x16x32_bf16 v[38:41], v[172:175], v[160:163], 0
	s_addk_i32 m0, 0x2000
	v_mfma_f32_16x16x32_bf16 v[34:37], v[172:175], v[164:167], 0
	s_waitcnt lgkmcnt(6)
	v_mfma_f32_16x16x32_bf16 v[30:33], v[176:179], v[152:155], 0
	ds_read_b128 v[172:175], v0 offset:3072
	v_mfma_f32_16x16x32_bf16 v[26:29], v[176:179], v[156:159], 0
	global_load_lds_dwordx4 v136, s[22:23]
	v_mfma_f32_16x16x32_bf16 v[22:25], v[176:179], v[160:163], 0
	s_addk_i32 m0, 0x2000
	v_mfma_f32_16x16x32_bf16 v[18:21], v[176:179], v[164:167], 0
	s_waitcnt lgkmcnt(6)
	v_mfma_f32_16x16x32_bf16 v[14:17], v[192:195], v[152:155], 0
	ds_read_b128 v[152:155], v0 offset:5120
	v_mfma_f32_16x16x32_bf16 v[10:13], v[192:195], v[156:159], 0
	global_load_lds_dwordx4 v136, s[24:25]
	v_mfma_f32_16x16x32_bf16 v[6:9], v[192:195], v[160:163], 0
	v_mfma_f32_16x16x32_bf16 v[2:5], v[192:195], v[164:167], 0
	s_waitcnt lgkmcnt(2)
	v_mfma_f32_16x16x32_bf16 v[126:129], v[208:211], v[168:171], v[126:129]
	ds_read_b128 v[156:159], v0 offset:7168
	v_mfma_f32_16x16x32_bf16 v[122:125], v[208:211], v[196:199], v[122:125]
	v_mfma_f32_16x16x32_bf16 v[118:121], v[208:211], v[200:203], v[118:121]
	v_mfma_f32_16x16x32_bf16 v[114:117], v[208:211], v[204:207], v[114:117]
	s_waitcnt lgkmcnt(2)
	v_mfma_f32_16x16x32_bf16 v[110:113], v[172:175], v[168:171], v[110:113]
	ds_read_b128 v[160:163], v0 offset:9216
	v_mfma_f32_16x16x32_bf16 v[106:109], v[172:175], v[196:199], v[106:109]
	v_mfma_f32_16x16x32_bf16 v[102:105], v[172:175], v[200:203], v[102:105]
	v_mfma_f32_16x16x32_bf16 v[98:101], v[172:175], v[204:207], v[98:101]
	s_waitcnt lgkmcnt(2)
	v_mfma_f32_16x16x32_bf16 v[94:97], v[152:155], v[168:171], v[94:97]
	ds_read_b128 v[164:167], v0 offset:11264
	v_mfma_f32_16x16x32_bf16 v[90:93], v[152:155], v[196:199], v[90:93]
	v_mfma_f32_16x16x32_bf16 v[86:89], v[152:155], v[200:203], v[86:89]
	v_mfma_f32_16x16x32_bf16 v[82:85], v[152:155], v[204:207], v[82:85]
	s_waitcnt lgkmcnt(2)
	v_mfma_f32_16x16x32_bf16 v[78:81], v[156:159], v[168:171], v[78:81]
	ds_read_b128 v[152:155], v0 offset:13312
	v_mfma_f32_16x16x32_bf16 v[74:77], v[156:159], v[196:199], v[74:77]
	v_mfma_f32_16x16x32_bf16 v[70:73], v[156:159], v[200:203], v[70:73]
	v_mfma_f32_16x16x32_bf16 v[66:69], v[156:159], v[204:207], v[66:69]
	s_waitcnt lgkmcnt(2)
	v_mfma_f32_16x16x32_bf16 v[62:65], v[160:163], v[168:171], v[62:65]
	ds_read_b128 v[156:159], v0 offset:15360
	v_mfma_f32_16x16x32_bf16 v[58:61], v[160:163], v[196:199], v[58:61]
	v_mfma_f32_16x16x32_bf16 v[54:57], v[160:163], v[200:203], v[54:57]
	v_mfma_f32_16x16x32_bf16 v[50:53], v[160:163], v[204:207], v[50:53]
	s_waitcnt lgkmcnt(2)
	v_mfma_f32_16x16x32_bf16 v[46:49], v[164:167], v[168:171], v[46:49]
	v_mfma_f32_16x16x32_bf16 v[42:45], v[164:167], v[196:199], v[42:45]
	v_mfma_f32_16x16x32_bf16 v[38:41], v[164:167], v[200:203], v[38:41]
	v_mfma_f32_16x16x32_bf16 v[34:37], v[164:167], v[204:207], v[34:37]
	s_waitcnt lgkmcnt(1)
	v_mfma_f32_16x16x32_bf16 v[30:33], v[152:155], v[168:171], v[30:33]
	v_mfma_f32_16x16x32_bf16 v[26:29], v[152:155], v[196:199], v[26:29]
	v_mfma_f32_16x16x32_bf16 v[22:25], v[152:155], v[200:203], v[22:25]
	v_mfma_f32_16x16x32_bf16 v[18:21], v[152:155], v[204:207], v[18:21]
	s_waitcnt lgkmcnt(0)
	v_mfma_f32_16x16x32_bf16 v[14:17], v[156:159], v[168:171], v[14:17]
	v_mfma_f32_16x16x32_bf16 v[10:13], v[156:159], v[196:199], v[10:13]
	v_mfma_f32_16x16x32_bf16 v[6:9], v[156:159], v[200:203], v[6:9]
	v_mfma_f32_16x16x32_bf16 v[2:5], v[156:159], v[204:207], v[2:5]
	s_nop 0
	s_add_i32 s5, s5, 0x10000
	s_add_u32 s12, s12, 0x80
	s_addc_u32 s13, s13, 0
	s_add_u32 s14, s14, 0x80
	s_addc_u32 s15, s15, 0
	s_add_u32 s16, s16, 0x80
	s_addc_u32 s17, s17, 0
	s_add_u32 s18, s18, 0x80
	s_addc_u32 s19, s19, 0
	s_add_u32 s20, s20, 0x80
	s_addc_u32 s21, s21, 0
	s_add_u32 s22, s22, 0x80
	s_addc_u32 s23, s23, 0
	s_add_u32 s24, s24, 0x80
	s_addc_u32 s25, s25, 0
	s_waitcnt vmcnt(0)
	s_add_u32 s26, s26, 0x80
	s_addc_u32 s27, s27, 0
	s_cmp_lg_u32 s37, s7
	s_waitcnt vmcnt(0)
	s_barrier
